# GLA D stage: native v_cvt_pk_bf16_f32 instead of the bfe/add3/perm round-to-nearest-even bit trick for 4 of 8 bf16 pairs (instruction selection)
# speedup vs baseline: 1.0018x; 1.0018x over previous
.LBB0_340:
	s_or_b64 exec, exec, s[0:1]
	s_waitcnt lgkmcnt(0)
	s_barrier
	ds_read_b128 v[52:55], v92 offset:9216
	ds_read_b128 v[60:63], v94
	ds_read_b128 v[48:51], v92
	s_nop 0
	s_nop 0
	ds_read_b128 v[68:71], v101
	ds_read_b128 v[56:59], v250 offset:16
	s_nop 0
	v_add_u32_e32 v81, v95, v103
	s_nop 0
	s_waitcnt lgkmcnt(4)
	v_cvt_f32_f16_sdwa v67, v52 dst_sel:DWORD dst_unused:UNUSED_PAD src0_sel:WORD_1
	s_nop 0
	s_waitcnt lgkmcnt(3)
	v_mul_f32_e32 v2, 0x3fb8aa3b, v60
	v_exp_f32_e32 v60, v2
	v_mul_f32_e32 v2, 0x3fb8aa3b, v61
	v_exp_f32_e32 v61, v2
	v_cvt_f32_f16_e32 v66, v52
	v_rcp_f32_e32 v64, v60
	v_add3_u32 v52, v78, v97, v247
	v_rcp_f32_e32 v65, v61
	v_cvt_f32_f16_sdwa v127, v54 dst_sel:DWORD dst_unused:UNUSED_PAD src0_sel:WORD_1
	v_cvt_f32_f16_e32 v126, v54
	v_pk_mul_f32 v[66:67], v[64:65], v[66:67]
	s_waitcnt lgkmcnt(2)
	v_cvt_f32_f16_sdwa v65, v48 dst_sel:DWORD dst_unused:UNUSED_PAD src0_sel:WORD_1
	v_cvt_f32_f16_e32 v64, v48
	s_nop 0
	s_waitcnt lgkmcnt(1)
	v_fma_mixlo_f16 v2, v68, v66, 0
	ds_write_b16 v52, v2 offset:46080
	v_fma_mixlo_f16 v2, v69, v67, 0
	v_pk_mul_f32 v[64:65], v[64:65], s[68:69] op_sel_hi:[1,0]
	ds_write_b16 v121, v2 offset:46080
	v_mul_f32_e32 v2, 0x3fb8aa3b, v62
	v_pk_mul_f32 v[64:65], v[64:65], v[60:61]
	v_exp_f32_e32 v60, v2
	v_mul_f32_e32 v2, 0x3fb8aa3b, v63
	v_exp_f32_e32 v61, v2
	v_cvt_f32_f16_sdwa v69, v53 dst_sel:DWORD dst_unused:UNUSED_PAD src0_sel:WORD_1
	v_rcp_f32_e32 v62, v60
	v_cvt_f32_f16_e32 v68, v53
	v_rcp_f32_e32 v63, v61
	v_cvt_f32_f16_sdwa v53, v49 dst_sel:DWORD dst_unused:UNUSED_PAD src0_sel:WORD_1
	v_cvt_f32_f16_e32 v52, v49
	v_cvt_pk_f16_f32 v48, v64, v65
	v_pk_mul_f32 v[68:69], v[62:63], v[68:69]
	v_pk_mul_f32 v[52:53], v[52:53], s[68:69] op_sel_hi:[1,0]
	v_fma_mixlo_f16 v2, v70, v68, 0
	ds_write_b16 v121, v2 offset:46224
	v_fma_mixlo_f16 v2, v71, v69, 0
	ds_write_b16 v121, v2 offset:46368
	s_waitcnt lgkmcnt(4)
	v_mul_f32_e32 v2, 0x3fb8aa3b, v56
	v_exp_f32_e32 v56, v2
	v_mul_f32_e32 v2, 0x3fb8aa3b, v57
	v_exp_f32_e32 v57, v2
	v_pk_mul_f32 v[52:53], v[52:53], v[60:61]
	ds_read_b128 v[60:63], v102
	v_rcp_f32_e32 v70, v56
	s_nop 0
	v_rcp_f32_e32 v71, v57
	v_cvt_pk_f16_f32 v49, v52, v53
	v_pk_mul_f32 v[70:71], v[70:71], v[126:127]
	s_nop 0
	s_waitcnt lgkmcnt(0)
	v_fma_mixlo_f16 v2, v60, v70, 0
	ds_write_b16 v121, v2 offset:46512
	v_fma_mixlo_f16 v2, v61, v71, 0
	ds_write_b16 v121, v2 offset:46656
	v_mul_f32_e32 v2, 0x3fb8aa3b, v58
	v_cvt_f32_f16_sdwa v127, v50 dst_sel:DWORD dst_unused:UNUSED_PAD src0_sel:WORD_1
	v_cvt_f32_f16_e32 v126, v50
	v_exp_f32_e32 v58, v2
	v_mul_f32_e32 v2, 0x3fb8aa3b, v59
	v_exp_f32_e32 v59, v2
	v_pk_mul_f32 v[126:127], v[126:127], s[68:69] op_sel_hi:[1,0]
	v_cvt_f32_f16_sdwa v61, v55 dst_sel:DWORD dst_unused:UNUSED_PAD src0_sel:WORD_1
	v_pk_mul_f32 v[126:127], v[126:127], v[56:57]
	v_rcp_f32_e32 v56, v58
	v_rcp_f32_e32 v57, v59
	v_cvt_f32_f16_e32 v60, v55
	s_nop 0
	s_nop 0
	v_cvt_pk_f16_f32 v50, v126, v127
	v_pk_mul_f32 v[128:129], v[56:57], v[60:61]
	s_nop 0
	v_fma_mixlo_f16 v2, v62, v128, 0
	ds_write_b16 v121, v2 offset:46800
	s_nop 0
	s_nop 0
	s_nop 0
	s_nop 0
	v_bfe_u32 v61, v67, 16, 1
	v_bfe_u32 v62, v66, 16, 1
	v_add3_u32 v62, v66, v62, s34
	v_add3_u32 v61, v67, v61, s34
	s_nop 0
	s_nop 0
	s_nop 0
	s_nop 0
	s_nop 0
	v_cvt_pk_bf16_f32 v57, v128, v129
	v_cvt_pk_bf16_f32 v56, v70, v71
	v_cvt_pk_bf16_f32 v55, v68, v69
	v_perm_b32 v54, v61, v62, s82
	v_cvt_f32_f16_sdwa v61, v51 dst_sel:DWORD dst_unused:UNUSED_PAD src0_sel:WORD_1
	v_cvt_f32_f16_e32 v60, v51
	s_nop 0
	v_bfe_u32 v66, v53, 16, 1
	v_bfe_u32 v67, v52, 16, 1
	v_pk_mul_f32 v[60:61], v[60:61], s[68:69] op_sel_hi:[1,0]
	v_bfe_u32 v68, v65, 16, 1
	v_pk_mul_f32 v[58:59], v[60:61], v[58:59]
	s_nop 0
	v_bfe_u32 v2, v59, 16, 1
	v_bfe_u32 v60, v58, 16, 1
	v_cvt_pk_f16_f32 v51, v58, v59
	v_bfe_u32 v69, v64, 16, 1
	v_add3_u32 v58, v58, v60, s34
	v_add3_u32 v2, v59, v2, s34
	v_add3_u32 v64, v64, v69, s34
	v_add3_u32 v65, v65, v68, s34
	v_add3_u32 v52, v52, v67, s34
	v_add3_u32 v53, v53, v66, s34
	s_nop 0
	s_nop 0
	v_perm_b32 v61, v2, v58, s82
	v_fma_mixlo_f16 v2, v63, v129, 0
	v_cvt_pk_bf16_f32 v60, v126, v127
	v_perm_b32 v59, v53, v52, s82
	v_perm_b32 v58, v65, v64, s82
	ds_write_b16 v121, v2 offset:46944
	ds_write_b128 v92, v[58:61] offset:18432
	ds_write_b128 v92, v[54:57] offset:27648
	ds_write_b128 v92, v[48:51] offset:36864
	v_add_u32_e32 v2, v79, v72
	s_nop 0
	s_barrier
	ds_read_b128 v[52:55], v81 offset:36864
	ds_read_b128 v[56:59], v81 offset:39168
	ds_read_b128 v[60:63], v81 offset:41472
	ds_read_b128 v[64:67], v81 offset:43776
	ds_read_b128 v[68:71], v2 offset:64
	ds_read_b128 v[178:181], v81 offset:36928
	ds_read_b128 v[182:185], v81 offset:39232
	ds_read_b128 v[186:189], v81 offset:41536
	ds_read_b128 v[48:51], v2
	s_nop 0
	s_nop 0
	s_nop 0
	s_nop 0
	s_nop 0
	s_waitcnt lgkmcnt(0)
	v_mfma_f32_16x16x32_f16 v[52:55], v[48:51], v[52:55], 0
	s_nop 0
	v_mfma_f32_16x16x32_f16 v[56:59], v[48:51], v[56:59], 0
	s_nop 0
	v_mfma_f32_16x16x32_f16 v[60:63], v[48:51], v[60:63], 0
	s_nop 0
	v_mfma_f32_16x16x32_f16 v[64:67], v[48:51], v[64:67], 0
	s_nop 0
	s_nop 0
	v_add_u32_e32 v2, v100, v72
	s_nop 0
	v_mfma_f32_16x16x32_f16 v[48:51], v[68:71], v[178:181], v[52:55]
	s_nop 2
	s_nop 0
	s_nop 0
	v_mfma_f32_16x16x32_f16 v[56:59], v[68:71], v[182:185], v[56:59]
	s_nop 0
	s_nop 0
	v_mfma_f32_16x16x32_f16 v[60:63], v[68:71], v[186:189], v[60:63]
	ds_read_b128 v[52:55], v81 offset:43840
	s_nop 0
	s_waitcnt lgkmcnt(0)
	v_mfma_f32_16x16x32_f16 v[64:67], v[68:71], v[52:55], v[64:67]
	v_mov_b32_e32 v52, 0
	v_mov_b32_e32 v68, 0
	v_mov_b32_e32 v69, 0
	v_mov_b32_e32 v70, 0
	v_mov_b32_e32 v71, 0
	s_and_saveexec_b64 s[0:1], s[6:7]
	s_cbranch_execz .LBB0_342
	v_add_u32_e32 v253, v95, v106
	ds_read_b128 v[68:71], v2 offset:18432
	ds_read_b128 v[126:129], v253 offset:27648
	v_add_u32_e32 v53, v95, v106
	s_nop 0
	s_nop 0
	s_nop 0
	s_waitcnt lgkmcnt(0)
	v_mfma_f32_16x16x32_bf16 v[68:71], v[126:129], v[68:71], 0
	ds_read_b128 v[130:133], v53 offset:27712
	ds_read_b128 v[126:129], v2 offset:18496
	s_nop 0
	s_nop 0
	s_waitcnt lgkmcnt(0)
	v_mfma_f32_16x16x32_bf16 v[68:71], v[130:133], v[126:129], v[68:71]

.LBB0_434:
	s_or_b64 exec, exec, s[0:1]
	v_add_u32_e32 v57, s78, v82
	v_add_u32_e32 v56, 0x7ff, v56
	v_cndmask_b32_e64 v56, v56, v57, s[2:3]
	s_waitcnt lgkmcnt(0)
	s_barrier
	ds_read_b128 v[58:61], v83
	ds_read_b128 v[62:65], v88
	ds_read_b128 v[48:51], v83 offset:9216
	s_nop 0
	ds_read_b128 v[66:69], v85
	ds_read_b128 v[52:55], v88 offset:9216
	v_lshrrev_b32_e32 v57, 6, v56
	v_and_b32_e32 v56, 63, v56
	v_cndmask_b32_e64 v56, v56, v57, s[6:7]
	v_lshl_or_b32 v57, v56, 6, v112
	s_nop 0
	v_add_u32_e32 v253, s83, v57
	ds_read_b128 v[122:125], v253
	ds_read_b128 v[118:121], v250 offset:16
	v_add_u32_e32 v75, s83, v57
	s_add_i32 s0, 0, 0x1f600
	v_add_u32_e32 v252, s0, v57
	ds_read_b128 v[126:129], v252
	v_add_u32_e32 v79, s0, v57
	s_waitcnt lgkmcnt(6)
	v_cvt_f32_f16_sdwa v137, v62 dst_sel:DWORD dst_unused:UNUSED_PAD src0_sel:WORD_1
	v_cvt_f32_f16_e32 v136, v62
	v_or_b32_e32 v57, 16, v57
	v_cvt_f32_f16_sdwa v135, v58 dst_sel:DWORD dst_unused:UNUSED_PAD src0_sel:WORD_1
	v_cvt_f32_f16_e32 v134, v58
	s_nop 0
	s_waitcnt lgkmcnt(4)
	v_mul_f32_e32 v56, 0x3fb8aa3b, v66
	v_add_u32_e32 v140, s83, v57
	ds_read_b128 v[130:133], v93
	v_add_u32_e32 v141, s0, v57
	v_mul_f32_e32 v57, 0x3fb8aa3b, v67
	v_exp_f32_e32 v56, v56
	v_exp_f32_e32 v57, v57
	v_pk_mul_f32 v[136:137], v[136:137], s[68:69] op_sel_hi:[1,0]
	v_pk_mul_f32 v[134:135], v[134:135], s[68:69] op_sel_hi:[1,0]
	s_nop 0
	s_waitcnt lgkmcnt(1)
	v_pk_mul_f32 v[136:137], v[136:137], v[126:127]
	v_rcp_f32_e32 v66, v56
	v_cndmask_b32_e64 v137, v137, -v137, s[8:9]
	v_cndmask_b32_e64 v136, v136, -v136, s[8:9]
	v_pk_fma_f32 v[134:135], v[134:135], v[122:123], v[136:137]
	v_cvt_f32_f16_sdwa v137, v48 dst_sel:DWORD dst_unused:UNUSED_PAD src0_sel:WORD_1
	v_pk_mul_f32 v[138:139], v[134:135], v[56:57]
	v_cvt_f32_f16_sdwa v135, v52 dst_sel:DWORD dst_unused:UNUSED_PAD src0_sel:WORD_1
	v_cvt_f32_f16_e32 v134, v52
	v_cvt_f32_f16_e32 v136, v48
	s_nop 0
	v_rcp_f32_e32 v67, v57
	v_pk_mul_f32 v[126:127], v[126:127], v[134:135]
	v_add3_u32 v52, v72, v89, v247
	v_cndmask_b32_e64 v127, v127, -v127, s[8:9]
	v_cndmask_b32_e64 v126, v126, -v126, s[8:9]
	v_pk_fma_f32 v[122:123], v[122:123], v[136:137], v[126:127]
	ds_read_b128 v[134:137], v94
	v_pk_mul_f32 v[126:127], v[122:123], v[66:67]
	v_cvt_f32_f16_e32 v58, v63
	s_nop 0
	s_waitcnt lgkmcnt(1)
	v_fma_mixlo_f16 v48, v130, v126, 0
	ds_write_b16 v52, v48 offset:46080
	v_fma_mixlo_f16 v48, v131, v127, 0
	ds_write_b16 v113, v48 offset:46080
	v_mul_f32_e32 v48, 0x3fb8aa3b, v68
	v_exp_f32_e32 v66, v48
	v_mul_f32_e32 v48, 0x3fb8aa3b, v69
	v_cvt_f32_f16_sdwa v69, v59 dst_sel:DWORD dst_unused:UNUSED_PAD src0_sel:WORD_1
	v_cvt_f32_f16_e32 v68, v59
	v_cvt_f32_f16_sdwa v59, v63 dst_sel:DWORD dst_unused:UNUSED_PAD src0_sel:WORD_1
	v_exp_f32_e32 v67, v48
	v_cvt_f32_f16_e32 v52, v49
	v_pk_mul_f32 v[68:69], v[68:69], s[68:69] op_sel_hi:[1,0]
	v_pk_mul_f32 v[58:59], v[58:59], s[68:69] op_sel_hi:[1,0]
	v_rcp_f32_e32 v62, v66
	v_pk_mul_f32 v[58:59], v[58:59], v[128:129]
	v_rcp_f32_e32 v63, v67
	v_cndmask_b32_e64 v59, v59, -v59, s[8:9]
	v_cndmask_b32_e64 v58, v58, -v58, s[8:9]
	v_pk_fma_f32 v[58:59], v[68:69], v[124:125], v[58:59]
	v_cvt_pk_f16_f32 v56, v138, v139
	v_pk_mul_f32 v[130:131], v[58:59], v[66:67]
	v_cvt_f32_f16_sdwa v59, v53 dst_sel:DWORD dst_unused:UNUSED_PAD src0_sel:WORD_1
	v_cvt_f32_f16_e32 v58, v53
	v_cvt_f32_f16_sdwa v53, v49 dst_sel:DWORD dst_unused:UNUSED_PAD src0_sel:WORD_1
	v_cvt_pk_f16_f32 v57, v130, v131
	v_pk_mul_f32 v[48:49], v[128:129], v[58:59]
	s_nop 0
	v_cndmask_b32_e64 v49, v49, -v49, s[8:9]
	v_cndmask_b32_e64 v48, v48, -v48, s[8:9]
	v_pk_fma_f32 v[48:49], v[124:125], v[52:53], v[48:49]
	v_cvt_f32_f16_sdwa v59, v60 dst_sel:DWORD dst_unused:UNUSED_PAD src0_sel:WORD_1
	v_pk_mul_f32 v[48:49], v[48:49], v[62:63]
	v_cvt_f32_f16_sdwa v63, v64 dst_sel:DWORD dst_unused:UNUSED_PAD src0_sel:WORD_1
	v_fma_mixlo_f16 v52, v132, v48, 0
	ds_write_b16 v113, v52 offset:46224
	v_fma_mixlo_f16 v52, v133, v49, 0
	ds_write_b16 v113, v52 offset:46368
	ds_read_b128 v[122:125], v141
	ds_read_b128 v[66:69], v140
	v_cvt_f32_f16_e32 v62, v64
	v_cvt_f32_f16_e32 v58, v60
	v_mul_f32_e32 v52, 0x3fb8aa3b, v118
	v_mul_f32_e32 v53, 0x3fb8aa3b, v119
	v_pk_mul_f32 v[62:63], v[62:63], s[68:69] op_sel_hi:[1,0]
	v_exp_f32_e32 v52, v52
	s_nop 0
	s_waitcnt lgkmcnt(1)
	v_pk_mul_f32 v[62:63], v[62:63], v[122:123]
	v_exp_f32_e32 v53, v53
	v_pk_mul_f32 v[58:59], v[58:59], s[68:69] op_sel_hi:[1,0]
	v_cndmask_b32_e64 v63, v63, -v63, s[8:9]
	v_cndmask_b32_e64 v62, v62, -v62, s[8:9]
	s_waitcnt lgkmcnt(0)
	v_pk_fma_f32 v[58:59], v[58:59], v[66:67], v[62:63]
	v_cvt_f32_f16_sdwa v63, v54 dst_sel:DWORD dst_unused:UNUSED_PAD src0_sel:WORD_1
	v_cvt_f32_f16_e32 v62, v54
	v_cvt_f32_f16_sdwa v129, v50 dst_sel:DWORD dst_unused:UNUSED_PAD src0_sel:WORD_1
	v_cvt_f32_f16_e32 v128, v50
	v_rcp_f32_e32 v118, v52
	v_rcp_f32_e32 v119, v53
	v_pk_mul_f32 v[62:63], v[122:123], v[62:63]
	v_cvt_f32_f16_e32 v60, v65
	v_cndmask_b32_e64 v63, v63, -v63, s[8:9]
	v_cndmask_b32_e64 v62, v62, -v62, s[8:9]
	v_pk_fma_f32 v[62:63], v[66:67], v[128:129], v[62:63]
	v_pk_mul_f32 v[52:53], v[58:59], v[52:53]
	v_pk_mul_f32 v[66:67], v[62:63], v[118:119]
	v_cvt_f32_f16_sdwa v119, v61 dst_sel:DWORD dst_unused:UNUSED_PAD src0_sel:WORD_1
	v_fma_mixlo_f16 v50, v134, v66, 0
	v_cvt_f32_f16_e32 v118, v61
	v_cvt_f32_f16_sdwa v61, v65 dst_sel:DWORD dst_unused:UNUSED_PAD src0_sel:WORD_1
	ds_write_b16 v113, v50 offset:46512
	v_fma_mixlo_f16 v50, v135, v67, 0
	ds_write_b16 v113, v50 offset:46656
	v_mul_f32_e32 v50, 0x3fb8aa3b, v120
	v_exp_f32_e32 v62, v50
	v_mul_f32_e32 v50, 0x3fb8aa3b, v121
	v_exp_f32_e32 v63, v50
	v_pk_mul_f32 v[60:61], v[60:61], s[68:69] op_sel_hi:[1,0]
	v_pk_mul_f32 v[118:119], v[118:119], s[68:69] op_sel_hi:[1,0]
	v_pk_mul_f32 v[60:61], v[60:61], v[124:125]
	v_rcp_f32_e32 v64, v62
	v_cndmask_b32_e64 v61, v61, -v61, s[8:9]
	v_cndmask_b32_e64 v60, v60, -v60, s[8:9]
	v_pk_fma_f32 v[60:61], v[118:119], v[68:69], v[60:61]
	v_rcp_f32_e32 v65, v63
	v_pk_mul_f32 v[60:61], v[60:61], v[62:63]
	s_nop 0
	s_nop 0
	v_bfe_u32 v75, v53, 16, 1
	v_bfe_u32 v79, v52, 16, 1
	v_cvt_pk_f16_f32 v58, v52, v53
	v_bfe_u32 v50, v61, 16, 1
	s_nop 0
	s_nop 0
	v_add3_u32 v52, v52, v79, s34
	v_add3_u32 v53, v53, v75, s34
	v_cvt_pk_f16_f32 v59, v60, v61
	v_bfe_u32 v54, v60, 16, 1
	v_add3_u32 v50, v61, v50, s34
	v_cvt_pk_bf16_f32 v61, v130, v131
	v_perm_b32 v62, v53, v52, s82
	v_cvt_f32_f16_sdwa v53, v55 dst_sel:DWORD dst_unused:UNUSED_PAD src0_sel:WORD_1
	v_cvt_f32_f16_e32 v52, v55
	v_add3_u32 v54, v60, v54, s34
	v_perm_b32 v63, v50, v54, s82
	v_cvt_f32_f16_sdwa v55, v51 dst_sel:DWORD dst_unused:UNUSED_PAD src0_sel:WORD_1
	v_cvt_f32_f16_e32 v54, v51
	v_pk_mul_f32 v[50:51], v[124:125], v[52:53]
	s_nop 0
	v_cndmask_b32_e64 v51, v51, -v51, s[8:9]
	v_cndmask_b32_e64 v50, v50, -v50, s[8:9]
	v_pk_fma_f32 v[50:51], v[68:69], v[54:55], v[50:51]
	s_nop 0
	v_pk_mul_f32 v[52:53], v[50:51], v[64:65]
	v_bfe_u32 v51, v48, 16, 1
	v_fma_mixlo_f16 v50, v136, v52, 0
	v_bfe_u32 v54, v53, 16, 1
	v_bfe_u32 v55, v52, 16, 1
	ds_write_b16 v113, v50 offset:46800
	v_bfe_u32 v50, v49, 16, 1
	s_nop 0
	s_nop 0
	s_nop 0
	s_nop 0
	v_add3_u32 v52, v52, v55, s34
	v_add3_u32 v54, v53, v54, s34
	s_nop 0
	s_nop 0
	v_add3_u32 v48, v48, v51, s34
	v_add3_u32 v49, v49, v50, s34
	s_nop 0
	s_nop 0
	s_nop 0
	s_nop 0
	v_perm_b32 v51, v54, v52, s82
	v_fma_mixlo_f16 v52, v137, v53, 0
	v_cvt_pk_bf16_f32 v60, v138, v139
	v_perm_b32 v49, v49, v48, s82
	v_cvt_pk_bf16_f32 v50, v66, v67
	v_cvt_pk_bf16_f32 v48, v126, v127
	ds_write_b16 v113, v52 offset:46944
	ds_write_b128 v83, v[60:63] offset:18432
	ds_write_b128 v83, v[48:51] offset:27648
	ds_write_b128 v83, v[56:59] offset:36864
	v_add_u32_e32 v56, v73, v0
	s_nop 0
	s_barrier
	v_add_u32_e32 v253, v86, v95
	ds_read_b128 v[52:55], v253 offset:36864
	ds_read_b128 v[64:67], v56 offset:64
	ds_read_b128 v[178:181], v253 offset:36928
	ds_read_b128 v[60:63], v253 offset:39168
	ds_read_b128 v[118:121], v253 offset:39232
	ds_read_b128 v[122:125], v253 offset:41472
	ds_read_b128 v[126:129], v253 offset:41536
	ds_read_b128 v[130:133], v253 offset:43776
	ds_read_b128 v[134:137], v253 offset:43840
	ds_read_b128 v[48:51], v56
	v_add_u32_e32 v68, v86, v95
	s_waitcnt lgkmcnt(0)
	v_mfma_f32_16x16x32_f16 v[52:55], v[48:51], v[52:55], 0
	v_add_u32_e32 v75, v92, v0
	v_mov_b32_e32 v68, 0
	v_mov_b32_e32 v69, 0
	s_nop 0
	v_mfma_f32_16x16x32_f16 v[60:63], v[48:51], v[60:63], 0
	s_nop 0
	v_mfma_f32_16x16x32_f16 v[122:125], v[48:51], v[122:125], 0
	s_nop 0
	v_mfma_f32_16x16x32_f16 v[48:51], v[48:51], v[130:133], 0
	v_mfma_f32_16x16x32_f16 v[52:55], v[64:67], v[178:181], v[52:55]
	v_mfma_f32_16x16x32_f16 v[56:59], v[64:67], v[118:121], v[60:63]
	v_mfma_f32_16x16x32_f16 v[60:63], v[64:67], v[126:129], v[122:125]
	s_nop 0
	v_mfma_f32_16x16x32_f16 v[48:51], v[64:67], v[134:137], v[48:51]
	v_mov_b32_e32 v64, 0
	v_mov_b32_e32 v66, 0
	v_mov_b32_e32 v67, 0
	s_and_saveexec_b64 s[0:1], s[10:11]
	s_cbranch_execz .LBB0_436
	v_add_u32_e32 v253, v86, v98
	ds_read_b128 v[66:69], v75 offset:18432
	ds_read_b128 v[118:121], v253 offset:27648
	v_add_u32_e32 v65, v86, v98
	s_nop 0
	s_nop 0
	s_nop 0
	s_waitcnt lgkmcnt(0)
	v_mfma_f32_16x16x32_bf16 v[66:69], v[118:121], v[66:69], 0
	ds_read_b128 v[122:125], v65 offset:27712
	ds_read_b128 v[118:121], v75 offset:18496
	s_nop 0
	s_nop 0
	s_waitcnt lgkmcnt(0)
	v_mfma_f32_16x16x32_bf16 v[66:69], v[122:125], v[118:121], v[66:69]

.LBB0_913:
	s_or_b64 exec, exec, s[0:1]
	s_waitcnt lgkmcnt(0)
	s_barrier
	ds_read_b128 v[52:55], v92 offset:9216
	ds_read_b128 v[60:63], v94
	ds_read_b128 v[48:51], v92
	s_nop 0
	s_nop 0
	ds_read_b128 v[68:71], v101
	ds_read_b128 v[56:59], v250 offset:16
	s_nop 0
	v_add_u32_e32 v81, v95, v103
	s_nop 0
	s_waitcnt lgkmcnt(4)
	v_cvt_f32_f16_sdwa v67, v52 dst_sel:DWORD dst_unused:UNUSED_PAD src0_sel:WORD_1
	s_nop 0
	s_waitcnt lgkmcnt(3)
	v_mul_f32_e32 v2, 0x3fb8aa3b, v60
	v_exp_f32_e32 v60, v2
	v_mul_f32_e32 v2, 0x3fb8aa3b, v61
	v_exp_f32_e32 v61, v2
	v_cvt_f32_f16_e32 v66, v52
	v_rcp_f32_e32 v64, v60
	v_add3_u32 v52, v78, v97, v247
	v_rcp_f32_e32 v65, v61
	v_cvt_f32_f16_sdwa v127, v54 dst_sel:DWORD dst_unused:UNUSED_PAD src0_sel:WORD_1
	v_cvt_f32_f16_e32 v126, v54
	v_pk_mul_f32 v[66:67], v[64:65], v[66:67]
	s_waitcnt lgkmcnt(2)
	v_cvt_f32_f16_sdwa v65, v48 dst_sel:DWORD dst_unused:UNUSED_PAD src0_sel:WORD_1
	v_cvt_f32_f16_e32 v64, v48
	s_nop 0
	s_waitcnt lgkmcnt(1)
	v_fma_mixlo_f16 v2, v68, v66, 0
	ds_write_b16 v52, v2 offset:46080
	v_fma_mixlo_f16 v2, v69, v67, 0
	v_pk_mul_f32 v[64:65], v[64:65], s[72:73] op_sel_hi:[1,0]
	ds_write_b16 v121, v2 offset:46080
	v_mul_f32_e32 v2, 0x3fb8aa3b, v62
	v_pk_mul_f32 v[64:65], v[64:65], v[60:61]
	v_exp_f32_e32 v60, v2
	v_mul_f32_e32 v2, 0x3fb8aa3b, v63
	v_exp_f32_e32 v61, v2
	v_cvt_f32_f16_sdwa v69, v53 dst_sel:DWORD dst_unused:UNUSED_PAD src0_sel:WORD_1
	v_rcp_f32_e32 v62, v60
	v_cvt_f32_f16_e32 v68, v53
	v_rcp_f32_e32 v63, v61
	v_cvt_f32_f16_sdwa v53, v49 dst_sel:DWORD dst_unused:UNUSED_PAD src0_sel:WORD_1
	v_cvt_f32_f16_e32 v52, v49
	v_cvt_pk_f16_f32 v48, v64, v65
	v_pk_mul_f32 v[68:69], v[62:63], v[68:69]
	v_pk_mul_f32 v[52:53], v[52:53], s[72:73] op_sel_hi:[1,0]
	v_fma_mixlo_f16 v2, v70, v68, 0
	ds_write_b16 v121, v2 offset:46224
	v_fma_mixlo_f16 v2, v71, v69, 0
	ds_write_b16 v121, v2 offset:46368
	s_waitcnt lgkmcnt(4)
	v_mul_f32_e32 v2, 0x3fb8aa3b, v56
	v_exp_f32_e32 v56, v2
	v_mul_f32_e32 v2, 0x3fb8aa3b, v57
	v_exp_f32_e32 v57, v2
	v_pk_mul_f32 v[52:53], v[52:53], v[60:61]
	ds_read_b128 v[60:63], v102
	v_rcp_f32_e32 v70, v56
	s_nop 0
	v_rcp_f32_e32 v71, v57
	v_cvt_pk_f16_f32 v49, v52, v53
	v_pk_mul_f32 v[70:71], v[70:71], v[126:127]
	s_nop 0
	s_waitcnt lgkmcnt(0)
	v_fma_mixlo_f16 v2, v60, v70, 0
	ds_write_b16 v121, v2 offset:46512
	v_fma_mixlo_f16 v2, v61, v71, 0
	ds_write_b16 v121, v2 offset:46656
	v_mul_f32_e32 v2, 0x3fb8aa3b, v58
	v_cvt_f32_f16_sdwa v127, v50 dst_sel:DWORD dst_unused:UNUSED_PAD src0_sel:WORD_1
	v_cvt_f32_f16_e32 v126, v50
	v_exp_f32_e32 v58, v2
	v_mul_f32_e32 v2, 0x3fb8aa3b, v59
	v_exp_f32_e32 v59, v2
	v_pk_mul_f32 v[126:127], v[126:127], s[72:73] op_sel_hi:[1,0]
	v_cvt_f32_f16_sdwa v61, v55 dst_sel:DWORD dst_unused:UNUSED_PAD src0_sel:WORD_1
	v_pk_mul_f32 v[126:127], v[126:127], v[56:57]
	v_rcp_f32_e32 v56, v58
	v_rcp_f32_e32 v57, v59
	v_cvt_f32_f16_e32 v60, v55
	s_nop 0
	s_nop 0
	v_cvt_pk_f16_f32 v50, v126, v127
	v_pk_mul_f32 v[128:129], v[56:57], v[60:61]
	s_nop 0
	v_fma_mixlo_f16 v2, v62, v128, 0
	ds_write_b16 v121, v2 offset:46800
	s_nop 0
	s_nop 0
	s_nop 0
	s_nop 0
	v_bfe_u32 v61, v67, 16, 1
	v_bfe_u32 v62, v66, 16, 1
	v_add3_u32 v62, v66, v62, s34
	v_add3_u32 v61, v67, v61, s34
	s_nop 0
	s_nop 0
	s_nop 0
	s_nop 0
	s_nop 0
	v_cvt_pk_bf16_f32 v57, v128, v129
	v_cvt_pk_bf16_f32 v56, v70, v71
	v_cvt_pk_bf16_f32 v55, v68, v69
	v_perm_b32 v54, v61, v62, s35
	v_cvt_f32_f16_sdwa v61, v51 dst_sel:DWORD dst_unused:UNUSED_PAD src0_sel:WORD_1
	v_cvt_f32_f16_e32 v60, v51
	s_nop 0
	v_bfe_u32 v66, v53, 16, 1
	v_bfe_u32 v67, v52, 16, 1
	v_pk_mul_f32 v[60:61], v[60:61], s[72:73] op_sel_hi:[1,0]
	v_bfe_u32 v68, v65, 16, 1
	v_pk_mul_f32 v[58:59], v[60:61], v[58:59]
	s_nop 0
	v_bfe_u32 v2, v59, 16, 1
	v_bfe_u32 v60, v58, 16, 1
	v_cvt_pk_f16_f32 v51, v58, v59
	v_bfe_u32 v69, v64, 16, 1
	v_add3_u32 v58, v58, v60, s34
	v_add3_u32 v2, v59, v2, s34
	v_add3_u32 v64, v64, v69, s34
	v_add3_u32 v65, v65, v68, s34
	v_add3_u32 v52, v52, v67, s34
	v_add3_u32 v53, v53, v66, s34
	s_nop 0
	s_nop 0
	v_perm_b32 v61, v2, v58, s35
	v_fma_mixlo_f16 v2, v63, v129, 0
	v_cvt_pk_bf16_f32 v60, v126, v127
	v_perm_b32 v59, v53, v52, s35
	v_perm_b32 v58, v65, v64, s35
	ds_write_b16 v121, v2 offset:46944
	ds_write_b128 v92, v[58:61] offset:18432
	ds_write_b128 v92, v[54:57] offset:27648
	ds_write_b128 v92, v[48:51] offset:36864
	v_add_u32_e32 v2, v79, v72
	s_nop 0
	s_barrier
	ds_read_b128 v[52:55], v81 offset:36864
	ds_read_b128 v[56:59], v81 offset:39168
	ds_read_b128 v[60:63], v81 offset:41472
	ds_read_b128 v[64:67], v81 offset:43776
	ds_read_b128 v[68:71], v2 offset:64
	ds_read_b128 v[162:165], v81 offset:36928
	ds_read_b128 v[178:181], v81 offset:39232
	ds_read_b128 v[182:185], v81 offset:41536
	ds_read_b128 v[48:51], v2
	s_nop 0
	s_nop 0
	s_nop 0
	s_nop 0
	s_nop 0
	s_waitcnt lgkmcnt(0)
	v_mfma_f32_16x16x32_f16 v[52:55], v[48:51], v[52:55], 0
	s_nop 0
	v_mfma_f32_16x16x32_f16 v[56:59], v[48:51], v[56:59], 0
	s_nop 0
	v_mfma_f32_16x16x32_f16 v[60:63], v[48:51], v[60:63], 0
	s_nop 0
	v_mfma_f32_16x16x32_f16 v[64:67], v[48:51], v[64:67], 0
	s_nop 0
	s_nop 0
	v_add_u32_e32 v2, v100, v72
	s_nop 0
	v_mfma_f32_16x16x32_f16 v[48:51], v[68:71], v[162:165], v[52:55]
	s_nop 2
	s_nop 0
	s_nop 0
	v_mfma_f32_16x16x32_f16 v[56:59], v[68:71], v[178:181], v[56:59]
	s_nop 0
	s_nop 0
	v_mfma_f32_16x16x32_f16 v[60:63], v[68:71], v[182:185], v[60:63]
	ds_read_b128 v[52:55], v81 offset:43840
	s_nop 0
	s_waitcnt lgkmcnt(0)
	v_mfma_f32_16x16x32_f16 v[64:67], v[68:71], v[52:55], v[64:67]
	v_mov_b32_e32 v52, 0
	v_mov_b32_e32 v68, 0
	v_mov_b32_e32 v69, 0
	v_mov_b32_e32 v70, 0
	v_mov_b32_e32 v71, 0
	s_and_saveexec_b64 s[0:1], s[6:7]
	s_cbranch_execz .LBB0_915
	v_add_u32_e32 v243, v95, v106
	ds_read_b128 v[68:71], v2 offset:18432
	ds_read_b128 v[126:129], v243 offset:27648
	v_add_u32_e32 v53, v95, v106
	s_nop 0
	s_nop 0
	s_nop 0
	s_waitcnt lgkmcnt(0)
	v_mfma_f32_16x16x32_bf16 v[68:71], v[126:129], v[68:71], 0
	ds_read_b128 v[130:133], v53 offset:27712
	ds_read_b128 v[126:129], v2 offset:18496
	s_nop 0
	s_nop 0
	s_waitcnt lgkmcnt(0)
	v_mfma_f32_16x16x32_bf16 v[68:71], v[130:133], v[126:129], v[68:71]

.LBB0_1007:
	s_or_b64 exec, exec, s[0:1]
	v_add_u32_e32 v57, s80, v82
	v_add_u32_e32 v56, 0x7ff, v56
	v_cndmask_b32_e64 v56, v56, v57, s[2:3]
	s_waitcnt lgkmcnt(0)
	s_barrier
	ds_read_b128 v[58:61], v83
	ds_read_b128 v[62:65], v88
	ds_read_b128 v[48:51], v83 offset:9216
	s_nop 0
	ds_read_b128 v[66:69], v85
	ds_read_b128 v[52:55], v88 offset:9216
	v_lshrrev_b32_e32 v57, 6, v56
	v_and_b32_e32 v56, 63, v56
	v_cndmask_b32_e64 v56, v56, v57, s[6:7]
	v_lshl_or_b32 v57, v56, 6, v112
	s_nop 0
	v_add_u32_e32 v243, s81, v57
	ds_read_b128 v[122:125], v243
	ds_read_b128 v[118:121], v250 offset:16
	v_add_u32_e32 v75, s81, v57
	s_add_i32 s0, 0, 0x1f600
	v_add_u32_e32 v242, s0, v57
	ds_read_b128 v[126:129], v242
	v_add_u32_e32 v79, s0, v57
	s_waitcnt lgkmcnt(6)
	v_cvt_f32_f16_sdwa v137, v62 dst_sel:DWORD dst_unused:UNUSED_PAD src0_sel:WORD_1
	v_cvt_f32_f16_e32 v136, v62
	v_or_b32_e32 v57, 16, v57
	v_cvt_f32_f16_sdwa v135, v58 dst_sel:DWORD dst_unused:UNUSED_PAD src0_sel:WORD_1
	v_cvt_f32_f16_e32 v134, v58
	s_nop 0
	s_waitcnt lgkmcnt(4)
	v_mul_f32_e32 v56, 0x3fb8aa3b, v66
	v_add_u32_e32 v140, s81, v57
	ds_read_b128 v[130:133], v93
	v_add_u32_e32 v141, s0, v57
	v_mul_f32_e32 v57, 0x3fb8aa3b, v67
	v_exp_f32_e32 v56, v56
	v_exp_f32_e32 v57, v57
	v_pk_mul_f32 v[136:137], v[136:137], s[72:73] op_sel_hi:[1,0]
	v_pk_mul_f32 v[134:135], v[134:135], s[72:73] op_sel_hi:[1,0]
	s_nop 0
	s_waitcnt lgkmcnt(1)
	v_pk_mul_f32 v[136:137], v[136:137], v[126:127]
	v_rcp_f32_e32 v66, v56
	v_cndmask_b32_e64 v137, v137, -v137, s[8:9]
	v_cndmask_b32_e64 v136, v136, -v136, s[8:9]
	v_pk_fma_f32 v[134:135], v[134:135], v[122:123], v[136:137]
	v_cvt_f32_f16_sdwa v137, v48 dst_sel:DWORD dst_unused:UNUSED_PAD src0_sel:WORD_1
	v_pk_mul_f32 v[138:139], v[134:135], v[56:57]
	v_cvt_f32_f16_sdwa v135, v52 dst_sel:DWORD dst_unused:UNUSED_PAD src0_sel:WORD_1
	v_cvt_f32_f16_e32 v134, v52
	v_cvt_f32_f16_e32 v136, v48
	s_nop 0
	v_rcp_f32_e32 v67, v57
	v_pk_mul_f32 v[126:127], v[126:127], v[134:135]
	v_add3_u32 v52, v72, v89, v247
	v_cndmask_b32_e64 v127, v127, -v127, s[8:9]
	v_cndmask_b32_e64 v126, v126, -v126, s[8:9]
	v_pk_fma_f32 v[122:123], v[122:123], v[136:137], v[126:127]
	ds_read_b128 v[134:137], v94
	v_pk_mul_f32 v[126:127], v[122:123], v[66:67]
	v_cvt_f32_f16_e32 v58, v63
	s_nop 0
	s_waitcnt lgkmcnt(1)
	v_fma_mixlo_f16 v48, v130, v126, 0
	ds_write_b16 v52, v48 offset:46080
	v_fma_mixlo_f16 v48, v131, v127, 0
	ds_write_b16 v113, v48 offset:46080
	v_mul_f32_e32 v48, 0x3fb8aa3b, v68
	v_exp_f32_e32 v66, v48
	v_mul_f32_e32 v48, 0x3fb8aa3b, v69
	v_cvt_f32_f16_sdwa v69, v59 dst_sel:DWORD dst_unused:UNUSED_PAD src0_sel:WORD_1
	v_cvt_f32_f16_e32 v68, v59
	v_cvt_f32_f16_sdwa v59, v63 dst_sel:DWORD dst_unused:UNUSED_PAD src0_sel:WORD_1
	v_exp_f32_e32 v67, v48
	v_cvt_f32_f16_e32 v52, v49
	v_pk_mul_f32 v[68:69], v[68:69], s[72:73] op_sel_hi:[1,0]
	v_pk_mul_f32 v[58:59], v[58:59], s[72:73] op_sel_hi:[1,0]
	v_rcp_f32_e32 v62, v66
	v_pk_mul_f32 v[58:59], v[58:59], v[128:129]
	v_rcp_f32_e32 v63, v67
	v_cndmask_b32_e64 v59, v59, -v59, s[8:9]
	v_cndmask_b32_e64 v58, v58, -v58, s[8:9]
	v_pk_fma_f32 v[58:59], v[68:69], v[124:125], v[58:59]
	v_cvt_pk_f16_f32 v56, v138, v139
	v_pk_mul_f32 v[130:131], v[58:59], v[66:67]
	v_cvt_f32_f16_sdwa v59, v53 dst_sel:DWORD dst_unused:UNUSED_PAD src0_sel:WORD_1
	v_cvt_f32_f16_e32 v58, v53
	v_cvt_f32_f16_sdwa v53, v49 dst_sel:DWORD dst_unused:UNUSED_PAD src0_sel:WORD_1
	v_cvt_pk_f16_f32 v57, v130, v131
	v_pk_mul_f32 v[48:49], v[128:129], v[58:59]
	s_nop 0
	v_cndmask_b32_e64 v49, v49, -v49, s[8:9]
	v_cndmask_b32_e64 v48, v48, -v48, s[8:9]
	v_pk_fma_f32 v[48:49], v[124:125], v[52:53], v[48:49]
	v_cvt_f32_f16_sdwa v59, v60 dst_sel:DWORD dst_unused:UNUSED_PAD src0_sel:WORD_1
	v_pk_mul_f32 v[48:49], v[48:49], v[62:63]
	v_cvt_f32_f16_sdwa v63, v64 dst_sel:DWORD dst_unused:UNUSED_PAD src0_sel:WORD_1
	v_fma_mixlo_f16 v52, v132, v48, 0
	ds_write_b16 v113, v52 offset:46224
	v_fma_mixlo_f16 v52, v133, v49, 0
	ds_write_b16 v113, v52 offset:46368
	ds_read_b128 v[122:125], v141
	ds_read_b128 v[66:69], v140
	v_cvt_f32_f16_e32 v62, v64
	v_cvt_f32_f16_e32 v58, v60
	v_mul_f32_e32 v52, 0x3fb8aa3b, v118
	v_mul_f32_e32 v53, 0x3fb8aa3b, v119
	v_pk_mul_f32 v[62:63], v[62:63], s[72:73] op_sel_hi:[1,0]
	v_exp_f32_e32 v52, v52
	s_nop 0
	s_waitcnt lgkmcnt(1)
	v_pk_mul_f32 v[62:63], v[62:63], v[122:123]
	v_exp_f32_e32 v53, v53
	v_pk_mul_f32 v[58:59], v[58:59], s[72:73] op_sel_hi:[1,0]
	v_cndmask_b32_e64 v63, v63, -v63, s[8:9]
	v_cndmask_b32_e64 v62, v62, -v62, s[8:9]
	s_waitcnt lgkmcnt(0)
	v_pk_fma_f32 v[58:59], v[58:59], v[66:67], v[62:63]
	v_cvt_f32_f16_sdwa v63, v54 dst_sel:DWORD dst_unused:UNUSED_PAD src0_sel:WORD_1
	v_cvt_f32_f16_e32 v62, v54
	v_cvt_f32_f16_sdwa v129, v50 dst_sel:DWORD dst_unused:UNUSED_PAD src0_sel:WORD_1
	v_cvt_f32_f16_e32 v128, v50
	v_rcp_f32_e32 v118, v52
	v_rcp_f32_e32 v119, v53
	v_pk_mul_f32 v[62:63], v[122:123], v[62:63]
	v_cvt_f32_f16_e32 v60, v65
	v_cndmask_b32_e64 v63, v63, -v63, s[8:9]
	v_cndmask_b32_e64 v62, v62, -v62, s[8:9]
	v_pk_fma_f32 v[62:63], v[66:67], v[128:129], v[62:63]
	v_pk_mul_f32 v[52:53], v[58:59], v[52:53]
	v_pk_mul_f32 v[66:67], v[62:63], v[118:119]
	v_cvt_f32_f16_sdwa v119, v61 dst_sel:DWORD dst_unused:UNUSED_PAD src0_sel:WORD_1
	v_fma_mixlo_f16 v50, v134, v66, 0
	v_cvt_f32_f16_e32 v118, v61
	v_cvt_f32_f16_sdwa v61, v65 dst_sel:DWORD dst_unused:UNUSED_PAD src0_sel:WORD_1
	ds_write_b16 v113, v50 offset:46512
	v_fma_mixlo_f16 v50, v135, v67, 0
	ds_write_b16 v113, v50 offset:46656
	v_mul_f32_e32 v50, 0x3fb8aa3b, v120
	v_exp_f32_e32 v62, v50
	v_mul_f32_e32 v50, 0x3fb8aa3b, v121
	v_exp_f32_e32 v63, v50
	v_pk_mul_f32 v[60:61], v[60:61], s[72:73] op_sel_hi:[1,0]
	v_pk_mul_f32 v[118:119], v[118:119], s[72:73] op_sel_hi:[1,0]
	v_pk_mul_f32 v[60:61], v[60:61], v[124:125]
	v_rcp_f32_e32 v64, v62
	v_cndmask_b32_e64 v61, v61, -v61, s[8:9]
	v_cndmask_b32_e64 v60, v60, -v60, s[8:9]
	v_pk_fma_f32 v[60:61], v[118:119], v[68:69], v[60:61]
	v_rcp_f32_e32 v65, v63
	v_pk_mul_f32 v[60:61], v[60:61], v[62:63]
	s_nop 0
	s_nop 0
	v_bfe_u32 v75, v53, 16, 1
	v_bfe_u32 v79, v52, 16, 1
	v_cvt_pk_f16_f32 v58, v52, v53
	v_bfe_u32 v50, v61, 16, 1
	s_nop 0
	s_nop 0
	v_add3_u32 v52, v52, v79, s34
	v_add3_u32 v53, v53, v75, s34
	v_cvt_pk_f16_f32 v59, v60, v61
	v_bfe_u32 v54, v60, 16, 1
	v_add3_u32 v50, v61, v50, s34
	v_cvt_pk_bf16_f32 v61, v130, v131
	v_perm_b32 v62, v53, v52, s35
	v_cvt_f32_f16_sdwa v53, v55 dst_sel:DWORD dst_unused:UNUSED_PAD src0_sel:WORD_1
	v_cvt_f32_f16_e32 v52, v55
	v_add3_u32 v54, v60, v54, s34
	v_perm_b32 v63, v50, v54, s35
	v_cvt_f32_f16_sdwa v55, v51 dst_sel:DWORD dst_unused:UNUSED_PAD src0_sel:WORD_1
	v_cvt_f32_f16_e32 v54, v51
	v_pk_mul_f32 v[50:51], v[124:125], v[52:53]
	s_nop 0
	v_cndmask_b32_e64 v51, v51, -v51, s[8:9]
	v_cndmask_b32_e64 v50, v50, -v50, s[8:9]
	v_pk_fma_f32 v[50:51], v[68:69], v[54:55], v[50:51]
	s_nop 0
	v_pk_mul_f32 v[52:53], v[50:51], v[64:65]
	v_bfe_u32 v51, v48, 16, 1
	v_fma_mixlo_f16 v50, v136, v52, 0
	v_bfe_u32 v54, v53, 16, 1
	v_bfe_u32 v55, v52, 16, 1
	ds_write_b16 v113, v50 offset:46800
	v_bfe_u32 v50, v49, 16, 1
	s_nop 0
	s_nop 0
	s_nop 0
	s_nop 0
	v_add3_u32 v52, v52, v55, s34
	v_add3_u32 v54, v53, v54, s34
	s_nop 0
	s_nop 0
	v_add3_u32 v48, v48, v51, s34
	v_add3_u32 v49, v49, v50, s34
	s_nop 0
	s_nop 0
	s_nop 0
	s_nop 0
	v_perm_b32 v51, v54, v52, s35
	v_fma_mixlo_f16 v52, v137, v53, 0
	v_cvt_pk_bf16_f32 v60, v138, v139
	v_perm_b32 v49, v49, v48, s35
	v_cvt_pk_bf16_f32 v50, v66, v67
	v_cvt_pk_bf16_f32 v48, v126, v127
	ds_write_b16 v113, v52 offset:46944
	ds_write_b128 v83, v[60:63] offset:18432
	ds_write_b128 v83, v[48:51] offset:27648
	ds_write_b128 v83, v[56:59] offset:36864
	v_add_u32_e32 v56, v73, v0
	s_nop 0
	s_barrier
	v_add_u32_e32 v243, v86, v95
	ds_read_b128 v[52:55], v243 offset:36864
	ds_read_b128 v[64:67], v56 offset:64
	ds_read_b128 v[162:165], v243 offset:36928
	ds_read_b128 v[60:63], v243 offset:39168
	ds_read_b128 v[118:121], v243 offset:39232
	ds_read_b128 v[122:125], v243 offset:41472
	ds_read_b128 v[126:129], v243 offset:41536
	ds_read_b128 v[130:133], v243 offset:43776
	ds_read_b128 v[134:137], v243 offset:43840
	ds_read_b128 v[48:51], v56
	v_add_u32_e32 v68, v86, v95
	s_waitcnt lgkmcnt(0)
	v_mfma_f32_16x16x32_f16 v[52:55], v[48:51], v[52:55], 0
	v_add_u32_e32 v75, v92, v0
	v_mov_b32_e32 v68, 0
	v_mov_b32_e32 v69, 0
	s_nop 0
	v_mfma_f32_16x16x32_f16 v[60:63], v[48:51], v[60:63], 0
	s_nop 0
	v_mfma_f32_16x16x32_f16 v[122:125], v[48:51], v[122:125], 0
	s_nop 0
	v_mfma_f32_16x16x32_f16 v[48:51], v[48:51], v[130:133], 0
	v_mfma_f32_16x16x32_f16 v[52:55], v[64:67], v[162:165], v[52:55]
	v_mfma_f32_16x16x32_f16 v[56:59], v[64:67], v[118:121], v[60:63]
	v_mfma_f32_16x16x32_f16 v[60:63], v[64:67], v[126:129], v[122:125]
	s_nop 0
	v_mfma_f32_16x16x32_f16 v[48:51], v[64:67], v[134:137], v[48:51]
	v_mov_b32_e32 v64, 0
	v_mov_b32_e32 v66, 0
	v_mov_b32_e32 v67, 0
	s_and_saveexec_b64 s[0:1], s[10:11]
	s_cbranch_execz .LBB0_1009
	v_add_u32_e32 v243, v86, v98
	ds_read_b128 v[66:69], v75 offset:18432
	ds_read_b128 v[118:121], v243 offset:27648
	v_add_u32_e32 v65, v86, v98
	s_nop 0
	s_nop 0
	s_nop 0
	s_waitcnt lgkmcnt(0)
	v_mfma_f32_16x16x32_bf16 v[66:69], v[118:121], v[66:69], 0
	ds_read_b128 v[122:125], v65 offset:27712
	ds_read_b128 v[118:121], v75 offset:18496
	s_nop 0
	s_nop 0
	s_waitcnt lgkmcnt(0)
	v_mfma_f32_16x16x32_bf16 v[66:69], v[122:125], v[118:121], v[66:69]
